# grid-barrier leader poll: 16 counter loads issued together with one wait instead of 15 serialized load-wait-add steps (8 sites), on top of no-sleep polling version
# speedup vs baseline: 1.0032x; 1.0032x over previous
.LBB0_203:
	v_readlane_b32 s4, v253, 21
	v_readlane_b32 s5, v253, 22
	s_waitcnt lgkmcnt(0)
	global_load_dword v0, v161, s[62:63] sc1
	s_mov_b64 s[18:19], -1
	s_mov_b64 s[24:25], -1
	s_nop 0
	global_load_dword v1, v161, s[4:5] sc1
	v_readlane_b32 s4, v253, 23
	v_readlane_b32 s5, v253, 24
	s_nop 4
	global_load_dword v2, v161, s[4:5] sc1
	v_readlane_b32 s4, v253, 25
	v_readlane_b32 s5, v253, 26
	s_nop 4
	global_load_dword v3, v161, s[4:5] sc1
	v_readlane_b32 s4, v253, 27
	v_readlane_b32 s5, v253, 28
	s_nop 4
	global_load_dword v4, v161, s[4:5] sc1
	v_readlane_b32 s4, v253, 29
	v_readlane_b32 s5, v253, 30
	s_nop 4
	global_load_dword v5, v161, s[4:5] sc1
	v_readlane_b32 s4, v253, 31
	v_readlane_b32 s5, v253, 32
	s_nop 4
	global_load_dword v6, v161, s[4:5] sc1
	v_readlane_b32 s4, v253, 33
	v_readlane_b32 s5, v253, 34
	s_nop 4
	global_load_dword v7, v161, s[4:5] sc1
	v_readlane_b32 s4, v253, 35
	v_readlane_b32 s5, v253, 36
	s_nop 4
	global_load_dword v8, v161, s[4:5] sc1
	v_readlane_b32 s4, v253, 37
	v_readlane_b32 s5, v253, 38
	s_nop 4
	global_load_dword v9, v161, s[4:5] sc1
	v_readlane_b32 s4, v253, 39
	v_readlane_b32 s5, v253, 40
	s_nop 4
	global_load_dword v10, v161, s[4:5] sc1
	v_readlane_b32 s4, v253, 41
	v_readlane_b32 s5, v253, 42
	s_nop 4
	global_load_dword v11, v161, s[4:5] sc1
	v_readlane_b32 s4, v253, 43
	v_readlane_b32 s5, v253, 44
	s_nop 4
	global_load_dword v12, v161, s[4:5] sc1
	v_readlane_b32 s4, v253, 45
	v_readlane_b32 s5, v253, 46
	s_nop 4
	global_load_dword v13, v161, s[4:5] sc1
	v_readlane_b32 s4, v253, 47
	v_readlane_b32 s5, v253, 48
	s_nop 4
	global_load_dword v14, v161, s[4:5] sc1
	v_readlane_b32 s4, v253, 49
	v_readlane_b32 s5, v253, 50
	s_nop 4
	global_load_dword v15, v161, s[4:5] sc1
	s_waitcnt vmcnt(0)
	v_add_u32_e32 v16, v1, v0
	v_add_u32_e32 v16, v16, v2
	v_add_u32_e32 v16, v16, v3
	v_add_u32_e32 v16, v16, v4
	v_add_u32_e32 v16, v16, v5
	v_add_u32_e32 v16, v16, v6
	v_add_u32_e32 v16, v16, v7
	v_add_u32_e32 v16, v16, v8
	v_add_u32_e32 v16, v16, v9
	v_add_u32_e32 v16, v16, v10
	v_add_u32_e32 v16, v16, v11
	v_add_u32_e32 v16, v16, v12
	v_add_u32_e32 v16, v16, v13
	v_add_u32_e32 v16, v16, v14
	v_add_u32_e32 v16, v16, v15
	v_cmp_eq_u32_e32 vcc, s83, v16
	s_cbranch_vccnz .LBB0_202
	s_and_b32 s1, s0, 0xff
	s_cmp_eq_u32 s1, 0
	s_mov_b64 s[34:35], -1
	s_cbranch_scc0 .LBB0_207
	global_load_dword v16, v161, s[96:97] sc1
	s_waitcnt vmcnt(0)
	v_cmp_eq_u32_e32 vcc, 0, v16
	s_cbranch_vccnz .LBB0_209
	s_mov_b64 s[34:35], 0

.LBB0_607:
	v_readlane_b32 s4, v253, 21
	v_readlane_b32 s5, v253, 22
	global_load_dword v0, v1, s[62:63] sc1
	s_mov_b64 s[24:25], -1
	s_mov_b64 s[34:35], -1
	s_waitcnt lgkmcnt(0)
	s_nop 0
	global_load_dword v2, v1, s[4:5] sc1
	v_readlane_b32 s4, v253, 23
	v_readlane_b32 s5, v253, 24
	s_nop 4
	global_load_dword v3, v1, s[4:5] sc1
	v_readlane_b32 s4, v253, 25
	v_readlane_b32 s5, v253, 26
	s_nop 4
	global_load_dword v4, v1, s[4:5] sc1
	v_readlane_b32 s4, v253, 27
	v_readlane_b32 s5, v253, 28
	s_nop 4
	global_load_dword v5, v1, s[4:5] sc1
	v_readlane_b32 s4, v253, 29
	v_readlane_b32 s5, v253, 30
	s_nop 4
	global_load_dword v6, v1, s[4:5] sc1
	v_readlane_b32 s4, v253, 31
	v_readlane_b32 s5, v253, 32
	s_nop 4
	global_load_dword v7, v1, s[4:5] sc1
	v_readlane_b32 s4, v253, 33
	v_readlane_b32 s5, v253, 34
	s_nop 4
	global_load_dword v8, v1, s[4:5] sc1
	v_readlane_b32 s4, v253, 35
	v_readlane_b32 s5, v253, 36
	s_nop 4
	global_load_dword v9, v1, s[4:5] sc1
	v_readlane_b32 s4, v253, 37
	v_readlane_b32 s5, v253, 38
	s_nop 4
	global_load_dword v10, v1, s[4:5] sc1
	v_readlane_b32 s4, v253, 39
	v_readlane_b32 s5, v253, 40
	s_nop 4
	global_load_dword v11, v1, s[4:5] sc1
	v_readlane_b32 s4, v253, 41
	v_readlane_b32 s5, v253, 42
	s_nop 4
	global_load_dword v12, v1, s[4:5] sc1
	v_readlane_b32 s4, v253, 43
	v_readlane_b32 s5, v253, 44
	s_nop 4
	global_load_dword v13, v1, s[4:5] sc1
	v_readlane_b32 s4, v253, 45
	v_readlane_b32 s5, v253, 46
	s_nop 4
	global_load_dword v14, v1, s[4:5] sc1
	v_readlane_b32 s4, v253, 47
	v_readlane_b32 s5, v253, 48
	s_nop 4
	global_load_dword v15, v1, s[4:5] sc1
	v_readlane_b32 s4, v253, 49
	v_readlane_b32 s5, v253, 50
	s_nop 4
	global_load_dword v16, v1, s[4:5] sc1
	s_waitcnt vmcnt(0)
	v_add_u32_e32 v17, v2, v0
	v_add_u32_e32 v17, v17, v3
	v_add_u32_e32 v17, v17, v4
	v_add_u32_e32 v17, v17, v5
	v_add_u32_e32 v17, v17, v6
	v_add_u32_e32 v17, v17, v7
	v_add_u32_e32 v17, v17, v8
	v_add_u32_e32 v17, v17, v9
	v_add_u32_e32 v17, v17, v10
	v_add_u32_e32 v17, v17, v11
	v_add_u32_e32 v17, v17, v12
	v_add_u32_e32 v17, v17, v13
	v_add_u32_e32 v17, v17, v14
	v_add_u32_e32 v17, v17, v15
	v_add_u32_e32 v17, v17, v16
	v_cmp_eq_u32_e32 vcc, s83, v17
	s_cbranch_vccnz .LBB0_606
	s_and_b32 s1, s0, 0xff
	s_cmp_eq_u32 s1, 0
	s_mov_b64 s[36:37], -1
	s_cbranch_scc0 .LBB0_611
	global_load_dword v17, v1, s[96:97] sc1
	s_waitcnt vmcnt(0)
	v_cmp_eq_u32_e32 vcc, 0, v17
	s_cbranch_vccnz .LBB0_613
	s_mov_b64 s[36:37], 0
